# layer-1 adaLN partial sums moved from P0 into layer-0 phase 6 (waves 0-3 of the attention/conversion workgroups, after their items); layer-1 modulation sums moved from phase 1 to the end of phase 7
# speedup vs baseline: 1.0074x; 1.0074x over previous
; #define EN(k) if constexpr (((PHASE_MASK) >> (k)) & 1)
; DI void mod_phase(const Params& P, int gw, int NGW, int lane) {
;     const float* MODP = (const float*)(P.ws + WS_MODP); float* MOD = (float*)(P.ws + WS_MOD);
;     for (int i = gw * 64 + lane; i < 2 * 2 * NMOD; i += NGW * 64) { const int l = i / (2 * NMOD), j = i % NMOD;
;         float s = P.b_ada[l * NMOD + j];
; #pragma unroll
;         for (int kc = 0; kc < 16; ++kc) s += MODP[(size_t)kc * (4 * NMOD) + i];
;         MOD[i] = s; }
; }
; __global__ void __launch_bounds__(512, 2) fwd_kernel(Params PK) {
;     ...
;         if (ph == 1) { EN(11) mod_phase(P, gw, NGW, lane); continue; }
.LBB0_78:
	v_readlane_b32 s48, v253, 55
	v_readlane_b32 s49, v253, 56
	s_mov_b64 s[4:5], s[24:25]
	s_mov_b64 s[0:1], s[26:27]
	s_mov_b64 s[8:9], s[48:49]
	v_readlane_b32 s57, v254, 0
	v_readlane_b32 s58, v254, 1
	v_readlane_b32 s59, v254, 2
	v_readlane_b32 s60, v254, 3
	v_readlane_b32 s61, v254, 4
	v_readlane_b32 s62, v254, 5
	v_readlane_b32 s63, v254, 6
	v_writelane_b32 v254, s8, 52
	v_mov_b32_e32 v241, v226
	v_readlane_b32 s50, v253, 57
	v_writelane_b32 v254, s9, 53
	v_writelane_b32 v254, s4, 54
	v_and_b32_e32 v240, 63, v241
	s_mov_b64 s[8:9], -1
	v_writelane_b32 v254, s5, 55
	v_writelane_b32 v254, s0, 56
	s_mov_b64 s[4:5], 0
	v_readlane_b32 s51, v253, 58
	v_writelane_b32 v254, s1, 57
	v_readfirstlane_b32 s0, v241
	s_ashr_i32 s6, s0, 6
	v_readlane_b32 s0, v253, 16
	s_add_i32 s18, s6, s0
	s_mov_b64 s[0:1], 0
	s_cmp_lt_i32 s28, 1
	v_readlane_b32 s52, v253, 59
	v_readlane_b32 s53, v253, 60
	v_readlane_b32 s54, v253, 61
	v_readlane_b32 s55, v253, 62
	v_readlane_b32 s56, v253, 63
	s_cbranch_scc1 .LBB0_103
	s_cmp_eq_u32 s28, 1
	s_mov_b64 s[4:5], -1
	s_cbranch_scc0 .LBB0_84
	s_waitcnt vmcnt(0)
	v_lshl_or_b32 v0, s18, 6, v240
	v_cmp_gt_i32_e32 vcc, 0x6000, v0
	s_and_saveexec_b64 s[4:5], vcc
	v_readlane_b32 s12, v253, 50
	v_readlane_b32 s13, v253, 51
	v_readlane_b32 s14, v253, 52
	v_readlane_b32 s48, v253, 55
	v_readlane_b32 s15, v253, 53
	v_readlane_b32 s58, v254, 1
	v_readlane_b32 s59, v254, 2
	s_movk_i32 s11, 0x3000
	s_mov_b32 s13, 0x210000
	v_readlane_b32 s49, v253, 56
	v_readlane_b32 s50, v253, 57
	v_readlane_b32 s51, v253, 58
	v_readlane_b32 s52, v253, 59
	v_readlane_b32 s53, v253, 60
	v_readlane_b32 s54, v253, 61
	v_readlane_b32 s55, v253, 62
	v_readlane_b32 s56, v253, 63
	v_readlane_b32 s57, v254, 0
	v_readlane_b32 s60, v254, 3
	v_readlane_b32 s61, v254, 4
	v_readlane_b32 s62, v254, 5
	v_readlane_b32 s63, v254, 6
	s_cbranch_execz .LBB0_83
	v_readlane_b32 s8, v254, 56
	v_ashrrev_i32_e32 v1, 31, v0
	v_readlane_b32 s9, v254, 57
	s_nop 1
	v_lshl_add_u64 v[2:3], v[0:1], 2, s[8:9]
	s_mov_b64 s[8:9], 0x2a200000
	v_lshl_add_u64 v[2:3], v[2:3], 0, s[8:9]
	s_mov_b64 s[8:9], 0

; DI void mod_phase(const Params& P, int gw, int NGW, int lane) {
;     ...
;     for (int i = gw * 64 + lane; i < 2 * 2 * NMOD; i += NGW * 64) { const int l = i / (2 * NMOD), j = i % NMOD;
;         float s = P.b_ada[l * NMOD + j];
; #pragma unroll
;         for (int kc = 0; kc < 16; ++kc) s += MODP[(size_t)kc * (4 * NMOD) + i];
;         MOD[i] = s; }
.LBB0_204:
	s_cmp_lg_u32 s28, 7
	s_cbranch_scc1 .Lmod1_skip
	v_readfirstlane_b32 s0, v241
	s_ashr_i32 s0, s0, 6
	v_readlane_b32 s1, v253, 16
	s_add_i32 s0, s0, s1
	s_cmpk_gt_i32 s0, 0x17f
	s_cbranch_scc1 .Lmod1_skip
	v_readlane_b32 s10, v254, 1
	v_readlane_b32 s11, v254, 2
	v_readlane_b32 s8, v254, 56
	v_readlane_b32 s9, v254, 57
	v_lshl_or_b32 v0, s0, 6, v240
	v_lshlrev_b32_e32 v2, 2, v0
	v_subrev_u32_e32 v3, 0x3000, v0
	v_cmp_gt_u32_e32 vcc, 0x3000, v0
	s_add_u32 s8, s8, 0x2a218000
	s_addc_u32 s9, s9, 0
	v_cndmask_b32_e32 v3, v3, v0, vcc
	v_add_u32_e32 v3, 0x3000, v3
	v_lshlrev_b32_e32 v3, 2, v3
	global_load_dword v1, v3, s[10:11]
	global_load_dword v4, v2, s[8:9]
	s_add_u32 s8, s8, 0x30000
	s_addc_u32 s9, s9, 0
	global_load_dword v5, v2, s[8:9]
	s_add_u32 s8, s8, 0x30000
	s_addc_u32 s9, s9, 0
	global_load_dword v6, v2, s[8:9]
	s_add_u32 s8, s8, 0x30000
	s_addc_u32 s9, s9, 0
	global_load_dword v7, v2, s[8:9]
	s_add_u32 s8, s8, 0x30000
	s_addc_u32 s9, s9, 0
	global_load_dword v8, v2, s[8:9]
	s_add_u32 s8, s8, 0x30000
	s_addc_u32 s9, s9, 0
	global_load_dword v9, v2, s[8:9]
	s_add_u32 s8, s8, 0x30000
	s_addc_u32 s9, s9, 0
	global_load_dword v10, v2, s[8:9]
	s_add_u32 s8, s8, 0x30000
	s_addc_u32 s9, s9, 0
	global_load_dword v11, v2, s[8:9]
	s_add_u32 s8, s8, 0x30000
	s_addc_u32 s9, s9, 0
	global_load_dword v12, v2, s[8:9]
	s_add_u32 s8, s8, 0x30000
	s_addc_u32 s9, s9, 0
	global_load_dword v13, v2, s[8:9]
	s_add_u32 s8, s8, 0x30000
	s_addc_u32 s9, s9, 0
	global_load_dword v14, v2, s[8:9]
	s_add_u32 s8, s8, 0x30000
	s_addc_u32 s9, s9, 0
	global_load_dword v15, v2, s[8:9]
	s_add_u32 s8, s8, 0x30000
	s_addc_u32 s9, s9, 0
	global_load_dword v16, v2, s[8:9]
	s_add_u32 s8, s8, 0x30000
	s_addc_u32 s9, s9, 0
	global_load_dword v17, v2, s[8:9]
	s_add_u32 s8, s8, 0x30000
	s_addc_u32 s9, s9, 0
	global_load_dword v18, v2, s[8:9]
	s_add_u32 s8, s8, 0x30000
	s_addc_u32 s9, s9, 0
	global_load_dword v19, v2, s[8:9]
	s_add_u32 s8, s8, 0x30000
	s_addc_u32 s9, s9, 0
	s_waitcnt vmcnt(0)
	v_add_f32_e32 v1, v1, v4
	v_add_f32_e32 v1, v1, v5
	v_add_f32_e32 v1, v1, v6
	v_add_f32_e32 v1, v1, v7
	v_add_f32_e32 v1, v1, v8
	v_add_f32_e32 v1, v1, v9
	v_add_f32_e32 v1, v1, v10
	v_add_f32_e32 v1, v1, v11
	v_add_f32_e32 v1, v1, v12
	v_add_f32_e32 v1, v1, v13
	v_add_f32_e32 v1, v1, v14
	v_add_f32_e32 v1, v1, v15
	v_add_f32_e32 v1, v1, v16
	v_add_f32_e32 v1, v1, v17
	v_add_f32_e32 v1, v1, v18
	v_add_f32_e32 v1, v1, v19
	global_store_dword v2, v1, s[8:9]

; DI void p0_phase(const Params& P, LAS unsigned char* lds, int gw, int NGW, int wave, int lane) {
;     ...
;     for (int it = gw; it < 2 * 16 * 48; it += NGW) {
;         const int cgp = it % 48, kc = (it / 48) % 16, l = it / 768, j0 = cgp * 256 + 4 * lane;
;         f32x4 a0 = {0.f, 0.f, 0.f, 0.f}, a1 = {0.f, 0.f, 0.f, 0.f};
;         const float* wp = P.w_ada + ((size_t)l * D + kc * 128) * NMOD + j0;
.LBB0_334:
	s_cmp_lg_u32 s28, 6
	s_cbranch_scc1 .Lada2_skip
	v_readfirstlane_b32 s0, v241
	s_ashr_i32 s1, s0, 6
	s_cmp_gt_i32 s1, 3
	s_cbranch_scc1 .Lada2_skip
	v_readlane_b32 s0, v253, 17
	s_lshr_b32 s0, s0, 1
	s_add_i32 s18, s0, s1
	s_addk_i32 s18, 0x300
	v_readlane_b32 s23, v254, 48

; DI float silu(float x) { return x * __builtin_amdgcn_rcpf(1.f + __expf(-x)); }
; DI void p0_phase(const Params& P, LAS unsigned char* lds, int gw, int NGW, int wave, int lane) {
;     ...
; #pragma unroll 8
;         for (int k = 0; k < 128; ++k) { const f32x4 w4 = *(const f32x4*)(wp + (size_t)k * NMOD);
;             const float c0 = silu(P.c[kc * 128 + k]), c1 = silu(P.c[D + kc * 128 + k]); a0 += w4 * c0; a1 += w4 * c1; }
;         *(f32x4*)(MODP + ((size_t)(kc * 2 + l) * 2 + 0) * NMOD + j0) = a0;
;         *(f32x4*)(MODP + ((size_t)(kc * 2 + l) * 2 + 1) * NMOD + j0) = a1;
.Lada2_last:
	s_waitcnt vmcnt(0)
	v_mul_f32_e32 v16, 0xbfb8aa3b, v144
	v_mul_f32_e32 v17, 0xbfb8aa3b, v148
	v_mul_f32_e32 v19, 0xbfb8aa3b, v145
	v_mul_f32_e32 v64, 0xbfb8aa3b, v149
	v_exp_f32_e32 v16, v16
	v_exp_f32_e32 v17, v17
	v_mul_f32_e32 v65, 0xbfb8aa3b, v146
	v_mul_f32_e32 v66, 0xbfb8aa3b, v150
	v_exp_f32_e32 v19, v19
	v_exp_f32_e32 v64, v64
	v_mul_f32_e32 v67, 0xbfb8aa3b, v147
	v_mul_f32_e32 v68, 0xbfb8aa3b, v151
	v_exp_f32_e32 v65, v65
	v_exp_f32_e32 v66, v66
	v_mul_f32_e32 v69, 0xbfb8aa3b, v152
	v_exp_f32_e32 v67, v67
	v_exp_f32_e32 v68, v68
	v_mul_f32_e32 v73, 0xbfb8aa3b, v160
	v_mul_f32_e32 v70, 0xbfb8aa3b, v153
	v_exp_f32_e32 v69, v69
	v_mul_f32_e32 v74, 0xbfb8aa3b, v161
	v_exp_f32_e32 v73, v73
	v_add_f32_e32 v16, 1.0, v16
	v_add_f32_e32 v17, 1.0, v17
	v_mul_f32_e32 v71, 0xbfb8aa3b, v154
	v_exp_f32_e32 v70, v70
	v_mul_f32_e32 v75, 0xbfb8aa3b, v162
	v_exp_f32_e32 v74, v74
	v_add_f32_e32 v19, 1.0, v19
	v_add_f32_e32 v64, 1.0, v64
	v_rcp_f32_e32 v16, v16
	v_rcp_f32_e32 v17, v17
	v_mul_f32_e32 v72, 0xbfb8aa3b, v155
	v_exp_f32_e32 v71, v71
	v_mul_f32_e32 v76, 0xbfb8aa3b, v163
	v_exp_f32_e32 v75, v75
	v_add_f32_e32 v65, 1.0, v65
	v_add_f32_e32 v66, 1.0, v66
	v_rcp_f32_e32 v19, v19
	v_rcp_f32_e32 v64, v64
	v_exp_f32_e32 v72, v72
	v_exp_f32_e32 v76, v76
	v_add_f32_e32 v67, 1.0, v67
	v_add_f32_e32 v68, 1.0, v68
	v_rcp_f32_e32 v65, v65
	v_rcp_f32_e32 v66, v66
	v_add_f32_e32 v69, 1.0, v69
	v_rcp_f32_e32 v67, v67
	v_rcp_f32_e32 v68, v68
	v_add_f32_e32 v73, 1.0, v73
	v_add_f32_e32 v70, 1.0, v70
	v_rcp_f32_e32 v69, v69
	v_add_f32_e32 v74, 1.0, v74
	v_rcp_f32_e32 v73, v73
	v_mul_f32_e32 v16, v144, v16
	v_mul_f32_e32 v144, v148, v17
	v_add_f32_e32 v71, 1.0, v71
	v_rcp_f32_e32 v70, v70
	v_add_f32_e32 v75, 1.0, v75
	v_rcp_f32_e32 v74, v74
	v_mul_f32_e32 v148, v145, v19
	v_mul_f32_e32 v64, v149, v64
	v_pk_fma_f32 v[4:5], v[156:157], v[16:17], v[4:5] op_sel_hi:[1,0,1]
	v_pk_fma_f32 v[6:7], v[158:159], v[16:17], v[6:7] op_sel_hi:[1,0,1]
	v_pk_fma_f32 v[0:1], v[156:157], v[144:145], v[0:1] op_sel_hi:[1,0,1]
	v_pk_fma_f32 v[2:3], v[158:159], v[144:145], v[2:3] op_sel_hi:[1,0,1]
	v_add_f32_e32 v72, 1.0, v72
	v_rcp_f32_e32 v71, v71
	v_add_f32_e32 v76, 1.0, v76
	v_rcp_f32_e32 v75, v75
	v_mul_f32_e32 v146, v146, v65
	v_mul_f32_e32 v150, v150, v66
	v_pk_fma_f32 v[6:7], v[122:123], v[148:149], v[6:7] op_sel_hi:[1,0,1]
	v_pk_fma_f32 v[4:5], v[120:121], v[148:149], v[4:5] op_sel_hi:[1,0,1]
	v_pk_fma_f32 v[2:3], v[122:123], v[64:65], v[2:3] op_sel_hi:[1,0,1]
	v_pk_fma_f32 v[0:1], v[120:121], v[64:65], v[0:1] op_sel_hi:[1,0,1]
	v_rcp_f32_e32 v72, v72
	v_rcp_f32_e32 v76, v76
	v_mul_f32_e32 v66, v147, v67
	v_mul_f32_e32 v68, v151, v68
	v_pk_fma_f32 v[6:7], v[126:127], v[146:147], v[6:7] op_sel_hi:[1,0,1]
	v_pk_fma_f32 v[4:5], v[124:125], v[146:147], v[4:5] op_sel_hi:[1,0,1]
	v_pk_fma_f32 v[2:3], v[126:127], v[150:151], v[2:3] op_sel_hi:[1,0,1]
	v_pk_fma_f32 v[0:1], v[124:125], v[150:151], v[0:1] op_sel_hi:[1,0,1]
	v_mul_f32_e32 v152, v152, v69
	v_mul_f32_e32 v16, v160, v73
	v_pk_fma_f32 v[6:7], v[130:131], v[66:67], v[6:7] op_sel_hi:[1,0,1]
	v_pk_fma_f32 v[4:5], v[128:129], v[66:67], v[4:5] op_sel_hi:[1,0,1]
	v_pk_fma_f32 v[2:3], v[130:131], v[68:69], v[2:3] op_sel_hi:[1,0,1]
	v_pk_fma_f32 v[0:1], v[128:129], v[68:69], v[0:1] op_sel_hi:[1,0,1]
	v_mul_f32_e32 v70, v153, v70
	v_mul_f32_e32 v120, v161, v74
	v_pk_fma_f32 v[6:7], v[110:111], v[152:153], v[6:7] op_sel_hi:[1,0,1]
	v_pk_fma_f32 v[4:5], v[108:109], v[152:153], v[4:5] op_sel_hi:[1,0,1]
	v_pk_fma_f32 v[2:3], v[110:111], v[16:17], v[2:3] op_sel_hi:[1,0,1]
	v_pk_fma_f32 v[0:1], v[108:109], v[16:17], v[0:1] op_sel_hi:[1,0,1]
	v_mul_f32_e32 v154, v154, v71
	v_mul_f32_e32 v122, v162, v75
	v_pk_fma_f32 v[6:7], v[134:135], v[70:71], v[6:7] op_sel_hi:[1,0,1]
	v_pk_fma_f32 v[4:5], v[132:133], v[70:71], v[4:5] op_sel_hi:[1,0,1]
	v_pk_fma_f32 v[2:3], v[134:135], v[120:121], v[2:3] op_sel_hi:[1,0,1]
	v_pk_fma_f32 v[0:1], v[132:133], v[120:121], v[0:1] op_sel_hi:[1,0,1]
	v_mul_f32_e32 v72, v155, v72
	v_mul_f32_e32 v144, v163, v76
	v_pk_fma_f32 v[6:7], v[138:139], v[154:155], v[6:7] op_sel_hi:[1,0,1]
	v_pk_fma_f32 v[4:5], v[136:137], v[154:155], v[4:5] op_sel_hi:[1,0,1]
	v_pk_fma_f32 v[2:3], v[138:139], v[122:123], v[2:3] op_sel_hi:[1,0,1]
	v_pk_fma_f32 v[0:1], v[136:137], v[122:123], v[0:1] op_sel_hi:[1,0,1]
	v_pk_fma_f32 v[6:7], v[142:143], v[72:73], v[6:7] op_sel_hi:[1,0,1]
	v_pk_fma_f32 v[4:5], v[140:141], v[72:73], v[4:5] op_sel_hi:[1,0,1]
	v_pk_fma_f32 v[2:3], v[142:143], v[144:145], v[2:3] op_sel_hi:[1,0,1]
	v_pk_fma_f32 v[0:1], v[140:141], v[144:145], v[0:1] op_sel_hi:[1,0,1]
	s_lshl_b32 s0, s11, 1
	s_add_i32 s0, s0, s12
	s_mul_hi_i32 s1, s0, 0x18000
	s_mul_i32 s0, s0, 0x18000
	s_add_u32 s0, s6, s0
	s_addc_u32 s1, s10, s1
	v_lshl_add_u64 v[8:9], v[12:13], 2, s[0:1]
	global_store_dwordx4 v[8:9], v[4:7], off
	s_add_i32 s18, s18, s23
	s_cmpk_gt_i32 s18, 0x5ff
	v_add_co_u32_e32 v4, vcc, 0xc000, v8
	s_nop 1
	v_addc_co_u32_e32 v5, vcc, 0, v9, vcc
	global_store_dwordx4 v[4:5], v[0:3], off
	s_cbranch_scc0 .Lada2_841
	v_readfirstlane_b32 s0, v241
	s_ashr_i32 s6, s0, 6
	v_readlane_b32 s0, v253, 16
	s_add_i32 s18, s6, s0

; DI float silu(float x) { return x * __builtin_amdgcn_rcpf(1.f + __expf(-x)); }
; DI void p0_phase(const Params& P, LAS unsigned char* lds, int gw, int NGW, int wave, int lane) {
;     ...
;     for (int it = gw; it < 2 * 16 * 48; it += NGW) {
;         const int cgp = it % 48, kc = (it / 48) % 16, l = it / 768, j0 = cgp * 256 + 4 * lane;
;         f32x4 a0 = {0.f, 0.f, 0.f, 0.f}, a1 = {0.f, 0.f, 0.f, 0.f};
;         const float* wp = P.w_ada + ((size_t)l * D + kc * 128) * NMOD + j0;
; #pragma unroll 8
;         for (int k = 0; k < 128; ++k) { const f32x4 w4 = *(const f32x4*)(wp + (size_t)k * NMOD);
;             const float c0 = silu(P.c[kc * 128 + k]), c1 = silu(P.c[D + kc * 128 + k]); a0 += w4 * c0; a1 += w4 * c1; }
;         *(f32x4*)(MODP + ((size_t)(kc * 2 + l) * 2 + 0) * NMOD + j0) = a0;
;         *(f32x4*)(MODP + ((size_t)(kc * 2 + l) * 2 + 1) * NMOD + j0) = a1;
;     }
.LBB0_839:
	s_or_b64 exec, exec, s[4:5]
	s_cmpk_gt_i32 s18, 0x2ff
	s_cbranch_scc0 .LBB0_840
	s_getpc_b64 s[98:99]

; DI float silu(float x) { return x * __builtin_amdgcn_rcpf(1.f + __expf(-x)); }
; DI void p0_phase(const Params& P, LAS unsigned char* lds, int gw, int NGW, int wave, int lane) {
;     ...
; #pragma unroll 8
;         for (int k = 0; k < 128; ++k) { const f32x4 w4 = *(const f32x4*)(wp + (size_t)k * NMOD);
;             const float c0 = silu(P.c[kc * 128 + k]), c1 = silu(P.c[D + kc * 128 + k]); a0 += w4 * c0; a1 += w4 * c1; }
;         *(f32x4*)(MODP + ((size_t)(kc * 2 + l) * 2 + 0) * NMOD + j0) = a0;
;         *(f32x4*)(MODP + ((size_t)(kc * 2 + l) * 2 + 1) * NMOD + j0) = a1;
;     }
.Ladaln_last:
	s_waitcnt vmcnt(0)
	v_mul_f32_e32 v16, 0xbfb8aa3b, v144
	v_mul_f32_e32 v17, 0xbfb8aa3b, v148
	v_mul_f32_e32 v19, 0xbfb8aa3b, v145
	v_mul_f32_e32 v64, 0xbfb8aa3b, v149
	v_exp_f32_e32 v16, v16
	v_exp_f32_e32 v17, v17
	v_mul_f32_e32 v65, 0xbfb8aa3b, v146
	v_mul_f32_e32 v66, 0xbfb8aa3b, v150
	v_exp_f32_e32 v19, v19
	v_exp_f32_e32 v64, v64
	v_mul_f32_e32 v67, 0xbfb8aa3b, v147
	v_mul_f32_e32 v68, 0xbfb8aa3b, v151
	v_exp_f32_e32 v65, v65
	v_exp_f32_e32 v66, v66
	v_mul_f32_e32 v69, 0xbfb8aa3b, v152
	v_exp_f32_e32 v67, v67
	v_exp_f32_e32 v68, v68
	v_mul_f32_e32 v73, 0xbfb8aa3b, v160
	v_mul_f32_e32 v70, 0xbfb8aa3b, v153
	v_exp_f32_e32 v69, v69
	v_mul_f32_e32 v74, 0xbfb8aa3b, v161
	v_exp_f32_e32 v73, v73
	v_add_f32_e32 v16, 1.0, v16
	v_add_f32_e32 v17, 1.0, v17
	v_mul_f32_e32 v71, 0xbfb8aa3b, v154
	v_exp_f32_e32 v70, v70
	v_mul_f32_e32 v75, 0xbfb8aa3b, v162
	v_exp_f32_e32 v74, v74
	v_add_f32_e32 v19, 1.0, v19
	v_add_f32_e32 v64, 1.0, v64
	v_rcp_f32_e32 v16, v16
	v_rcp_f32_e32 v17, v17
	v_mul_f32_e32 v72, 0xbfb8aa3b, v155
	v_exp_f32_e32 v71, v71
	v_mul_f32_e32 v76, 0xbfb8aa3b, v163
	v_exp_f32_e32 v75, v75
	v_add_f32_e32 v65, 1.0, v65
	v_add_f32_e32 v66, 1.0, v66
	v_rcp_f32_e32 v19, v19
	v_rcp_f32_e32 v64, v64
	v_exp_f32_e32 v72, v72
	v_exp_f32_e32 v76, v76
	v_add_f32_e32 v67, 1.0, v67
	v_add_f32_e32 v68, 1.0, v68
	v_rcp_f32_e32 v65, v65
	v_rcp_f32_e32 v66, v66
	v_add_f32_e32 v69, 1.0, v69
	v_rcp_f32_e32 v67, v67
	v_rcp_f32_e32 v68, v68
	v_add_f32_e32 v73, 1.0, v73
	v_add_f32_e32 v70, 1.0, v70
	v_rcp_f32_e32 v69, v69
	v_add_f32_e32 v74, 1.0, v74
	v_rcp_f32_e32 v73, v73
	v_mul_f32_e32 v16, v144, v16
	v_mul_f32_e32 v144, v148, v17
	v_add_f32_e32 v71, 1.0, v71
	v_rcp_f32_e32 v70, v70
	v_add_f32_e32 v75, 1.0, v75
	v_rcp_f32_e32 v74, v74
	v_mul_f32_e32 v148, v145, v19
	v_mul_f32_e32 v64, v149, v64
	v_pk_fma_f32 v[4:5], v[156:157], v[16:17], v[4:5] op_sel_hi:[1,0,1]
	v_pk_fma_f32 v[6:7], v[158:159], v[16:17], v[6:7] op_sel_hi:[1,0,1]
	v_pk_fma_f32 v[0:1], v[156:157], v[144:145], v[0:1] op_sel_hi:[1,0,1]
	v_pk_fma_f32 v[2:3], v[158:159], v[144:145], v[2:3] op_sel_hi:[1,0,1]
	v_add_f32_e32 v72, 1.0, v72
	v_rcp_f32_e32 v71, v71
	v_add_f32_e32 v76, 1.0, v76
	v_rcp_f32_e32 v75, v75
	v_mul_f32_e32 v146, v146, v65
	v_mul_f32_e32 v150, v150, v66
	v_pk_fma_f32 v[6:7], v[122:123], v[148:149], v[6:7] op_sel_hi:[1,0,1]
	v_pk_fma_f32 v[4:5], v[120:121], v[148:149], v[4:5] op_sel_hi:[1,0,1]
	v_pk_fma_f32 v[2:3], v[122:123], v[64:65], v[2:3] op_sel_hi:[1,0,1]
	v_pk_fma_f32 v[0:1], v[120:121], v[64:65], v[0:1] op_sel_hi:[1,0,1]
	v_rcp_f32_e32 v72, v72
	v_rcp_f32_e32 v76, v76
	v_mul_f32_e32 v66, v147, v67
	v_mul_f32_e32 v68, v151, v68
	v_pk_fma_f32 v[6:7], v[126:127], v[146:147], v[6:7] op_sel_hi:[1,0,1]
	v_pk_fma_f32 v[4:5], v[124:125], v[146:147], v[4:5] op_sel_hi:[1,0,1]
	v_pk_fma_f32 v[2:3], v[126:127], v[150:151], v[2:3] op_sel_hi:[1,0,1]
	v_pk_fma_f32 v[0:1], v[124:125], v[150:151], v[0:1] op_sel_hi:[1,0,1]
	v_mul_f32_e32 v152, v152, v69
	v_mul_f32_e32 v16, v160, v73
	v_pk_fma_f32 v[6:7], v[130:131], v[66:67], v[6:7] op_sel_hi:[1,0,1]
	v_pk_fma_f32 v[4:5], v[128:129], v[66:67], v[4:5] op_sel_hi:[1,0,1]
	v_pk_fma_f32 v[2:3], v[130:131], v[68:69], v[2:3] op_sel_hi:[1,0,1]
	v_pk_fma_f32 v[0:1], v[128:129], v[68:69], v[0:1] op_sel_hi:[1,0,1]
	v_mul_f32_e32 v70, v153, v70
	v_mul_f32_e32 v120, v161, v74
	v_pk_fma_f32 v[6:7], v[110:111], v[152:153], v[6:7] op_sel_hi:[1,0,1]
	v_pk_fma_f32 v[4:5], v[108:109], v[152:153], v[4:5] op_sel_hi:[1,0,1]
	v_pk_fma_f32 v[2:3], v[110:111], v[16:17], v[2:3] op_sel_hi:[1,0,1]
	v_pk_fma_f32 v[0:1], v[108:109], v[16:17], v[0:1] op_sel_hi:[1,0,1]
	v_mul_f32_e32 v154, v154, v71
	v_mul_f32_e32 v122, v162, v75
	v_pk_fma_f32 v[6:7], v[134:135], v[70:71], v[6:7] op_sel_hi:[1,0,1]
	v_pk_fma_f32 v[4:5], v[132:133], v[70:71], v[4:5] op_sel_hi:[1,0,1]
	v_pk_fma_f32 v[2:3], v[134:135], v[120:121], v[2:3] op_sel_hi:[1,0,1]
	v_pk_fma_f32 v[0:1], v[132:133], v[120:121], v[0:1] op_sel_hi:[1,0,1]
	v_mul_f32_e32 v72, v155, v72
	v_mul_f32_e32 v144, v163, v76
	v_pk_fma_f32 v[6:7], v[138:139], v[154:155], v[6:7] op_sel_hi:[1,0,1]
	v_pk_fma_f32 v[4:5], v[136:137], v[154:155], v[4:5] op_sel_hi:[1,0,1]
	v_pk_fma_f32 v[2:3], v[138:139], v[122:123], v[2:3] op_sel_hi:[1,0,1]
	v_pk_fma_f32 v[0:1], v[136:137], v[122:123], v[0:1] op_sel_hi:[1,0,1]
	v_pk_fma_f32 v[6:7], v[142:143], v[72:73], v[6:7] op_sel_hi:[1,0,1]
	v_pk_fma_f32 v[4:5], v[140:141], v[72:73], v[4:5] op_sel_hi:[1,0,1]
	v_pk_fma_f32 v[2:3], v[142:143], v[144:145], v[2:3] op_sel_hi:[1,0,1]
	v_pk_fma_f32 v[0:1], v[140:141], v[144:145], v[0:1] op_sel_hi:[1,0,1]
	s_lshl_b32 s0, s11, 1
	s_add_i32 s0, s0, s12
	s_mul_hi_i32 s1, s0, 0x18000
	s_mul_i32 s0, s0, 0x18000
	s_add_u32 s0, s6, s0
	s_addc_u32 s1, s10, s1
	v_lshl_add_u64 v[8:9], v[12:13], 2, s[0:1]
	global_store_dwordx4 v[8:9], v[4:7], off
	s_add_i32 s18, s18, s23
	s_cmpk_gt_i32 s18, 0x2ff
	v_add_co_u32_e32 v4, vcc, 0xc000, v8
	s_nop 1
	v_addc_co_u32_e32 v5, vcc, 0, v9, vcc
	global_store_dwordx4 v[4:5], v[0:3], off
	s_cbranch_scc0 .LBB0_841
	s_getpc_b64 s[98:99]
